# v25 with the 32 unneeded s_nop 0 in front of the gate/up epilogue stores removed
# speedup vs baseline: 1.0008x; 1.0008x over previous
; __device__ __forceinline__ unsigned pk2(float lo, float hi) { f32x2_t v = {lo, hi}; bf16x2_t b = __builtin_convertvector(v, bf16x2_t); return __builtin_bit_cast(unsigned, b); }
; __device__ __forceinline__ float sigm(float x) { return frcp(1.f + fexp2(-LOG2E * x)); }
;   __device__ __forceinline__ void operator()(const pg8::f32x4 (&acc)[2][2][4][2], const pg8::Unit& u, int wr, int wc, int fr, int fq) const {
;     int z; asm volatile("v_mov_b32 %0, 0" : "=v"(z));
;     const int row0 = u.pm * 256 + wr * 64 + fr + z, col0 = u.pn * 128 + wc * 32 + 8 * fq + z;
; #pragma unroll
;     for (int ai = 0; ai < 2; ++ai) {
;       float rs[4];
; #pragma unroll
;       for (int m = 0; m < 4; ++m) { const f32x4 a = *(const f32x4*)(ssq + (unsigned)(row0 + ai * 128 + m * 16) * 16 + 4 * fq); rs[m] = (a[0] + a[1]) + (a[2] + a[3]); }
; #pragma unroll
;       for (int m = 0; m < 4; ++m) { float v = rs[m]; v += __shfl_xor(v, 16); v += __shfl_xor(v, 32); rs[m] = rsqrtf(v * (1.f / 1024.f) + EPS); }
; #pragma unroll
;       for (int m = 0; m < 4; ++m) {
;         const float r = rs[m]; float v[8];
; #pragma unroll
;         for (int n = 0; n < 2; ++n)
; #pragma unroll
;           for (int c = 0; c < 4; ++c) { const float g = acc[ai][0][m][n][c] * r, uu = acc[ai][1][m][n][c] * r; v[4 * n + c] = g * sigm(g) * uu; }
;         u32x4 w; w.x = pk2(v[0], v[1]); w.y = pk2(v[2], v[3]); w.z = pk2(v[4], v[5]); w.w = pk2(v[6], v[7]);
;         *(u32x4*)(hbuf + (unsigned)(row0 + ai * 128 + m * 16) * DFF + col0) = w;
;       }
;       asm volatile("" ::: "memory");
;     }
;   }
.Lgu_181_havew:
	v_lshl_add_u64 v[242:243], v[240:241], 0, s[100:101]
	s_mov_b32 s100, 0x16000
	v_rsq_f32_e32 v188, v172
	v_rsq_f32_e32 v190, v174
	v_rsq_f32_e32 v192, v176
	v_rsq_f32_e32 v194, v178
	v_rsq_f32_e32 v196, v180
	v_rsq_f32_e32 v198, v182
	v_rsq_f32_e32 v200, v184
	v_rsq_f32_e32 v202, v186
	v_mul_f32_e32 v188, 0xbfb8aa3b, v188
	v_mul_f32_e32 v190, 0xbfb8aa3b, v190
	v_mul_f32_e32 v192, 0xbfb8aa3b, v192
	v_mul_f32_e32 v194, 0xbfb8aa3b, v194
	v_mul_f32_e32 v196, 0xbfb8aa3b, v196
	v_mul_f32_e32 v198, 0xbfb8aa3b, v198
	v_mul_f32_e32 v200, 0xbfb8aa3b, v200
	v_mul_f32_e32 v202, 0xbfb8aa3b, v202
	v_pk_mul_f32 v[228:229], v[124:125], v[188:189] op_sel_hi:[1,0]
	v_pk_mul_f32 v[230:231], v[126:127], v[188:189] op_sel_hi:[1,0]
	v_pk_mul_f32 v[232:233], v[116:117], v[188:189] op_sel_hi:[1,0]
	v_pk_mul_f32 v[234:235], v[118:119], v[188:189] op_sel_hi:[1,0]
	v_exp_f32_e32 v228, v228
	v_exp_f32_e32 v229, v229
	v_pk_mul_f32 v[124:125], v[124:125], v[120:121]
	v_exp_f32_e32 v230, v230
	v_exp_f32_e32 v231, v231
	v_pk_mul_f32 v[126:127], v[126:127], v[122:123]
	v_exp_f32_e32 v232, v232
	v_exp_f32_e32 v233, v233
	v_pk_mul_f32 v[116:117], v[116:117], v[112:113]
	v_exp_f32_e32 v234, v234
	v_exp_f32_e32 v235, v235
	v_pk_mul_f32 v[118:119], v[118:119], v[114:115]
	v_pk_fma_f32 v[228:229], v[228:229], v[172:173], v[172:173] op_sel_hi:[1,0,0]
	v_pk_fma_f32 v[230:231], v[230:231], v[172:173], v[172:173] op_sel_hi:[1,0,0]
	v_pk_fma_f32 v[232:233], v[232:233], v[172:173], v[172:173] op_sel_hi:[1,0,0]
	v_pk_fma_f32 v[234:235], v[234:235], v[172:173], v[172:173] op_sel_hi:[1,0,0]
	v_rcp_f32_e32 v228, v228
	v_pk_mul_f32 v[204:205], v[108:109], v[190:191] op_sel_hi:[1,0]
	v_rcp_f32_e32 v229, v229
	v_pk_mul_f32 v[206:207], v[110:111], v[190:191] op_sel_hi:[1,0]
	v_rcp_f32_e32 v230, v230
	v_pk_mul_f32 v[208:209], v[104:105], v[190:191] op_sel_hi:[1,0]
	v_rcp_f32_e32 v231, v231
	v_pk_mul_f32 v[210:211], v[106:107], v[190:191] op_sel_hi:[1,0]
	v_rcp_f32_e32 v232, v232
	v_pk_mul_f32 v[108:109], v[108:109], v[100:101]
	v_rcp_f32_e32 v233, v233
	v_pk_mul_f32 v[110:111], v[110:111], v[102:103]
	v_rcp_f32_e32 v234, v234
	v_pk_mul_f32 v[104:105], v[104:105], v[96:97]
	v_rcp_f32_e32 v235, v235
	v_pk_mul_f32 v[106:107], v[106:107], v[98:99]
	v_exp_f32_e32 v204, v204
	v_pk_mul_f32 v[124:125], v[124:125], v[228:229]
	v_exp_f32_e32 v205, v205
	v_pk_mul_f32 v[126:127], v[126:127], v[230:231]
	v_exp_f32_e32 v206, v206
	v_pk_mul_f32 v[116:117], v[116:117], v[232:233]
	v_exp_f32_e32 v207, v207
	v_pk_mul_f32 v[118:119], v[118:119], v[234:235]
	v_exp_f32_e32 v208, v208
	v_cvt_pk_bf16_f32 v236, v124, v125
	v_exp_f32_e32 v209, v209
	v_cvt_pk_bf16_f32 v237, v126, v127
	v_exp_f32_e32 v210, v210
	v_cvt_pk_bf16_f32 v238, v116, v117
	v_exp_f32_e32 v211, v211
	v_cvt_pk_bf16_f32 v239, v118, v119
	global_store_dwordx4 v[240:241], v[236:239], off
	v_lshl_add_u64 v[240:241], v[240:241], 0, s[100:101]
	v_pk_fma_f32 v[204:205], v[204:205], v[174:175], v[174:175] op_sel_hi:[1,0,0]
	v_pk_fma_f32 v[206:207], v[206:207], v[174:175], v[174:175] op_sel_hi:[1,0,0]
	v_pk_fma_f32 v[208:209], v[208:209], v[174:175], v[174:175] op_sel_hi:[1,0,0]
	v_pk_fma_f32 v[210:211], v[210:211], v[174:175], v[174:175] op_sel_hi:[1,0,0]
	v_rcp_f32_e32 v204, v204
	v_pk_mul_f32 v[228:229], v[92:93], v[192:193] op_sel_hi:[1,0]
	v_rcp_f32_e32 v205, v205
	v_pk_mul_f32 v[230:231], v[94:95], v[192:193] op_sel_hi:[1,0]
	v_rcp_f32_e32 v206, v206
	v_pk_mul_f32 v[232:233], v[88:89], v[192:193] op_sel_hi:[1,0]
	v_rcp_f32_e32 v207, v207
	v_pk_mul_f32 v[234:235], v[90:91], v[192:193] op_sel_hi:[1,0]
	v_rcp_f32_e32 v208, v208
	v_pk_mul_f32 v[92:93], v[92:93], v[84:85]
	v_rcp_f32_e32 v209, v209
	v_pk_mul_f32 v[94:95], v[94:95], v[86:87]
	v_rcp_f32_e32 v210, v210
	v_pk_mul_f32 v[88:89], v[88:89], v[80:81]
	v_rcp_f32_e32 v211, v211
	v_pk_mul_f32 v[90:91], v[90:91], v[82:83]
	v_exp_f32_e32 v228, v228
	v_pk_mul_f32 v[108:109], v[108:109], v[204:205]
	v_exp_f32_e32 v229, v229
	v_pk_mul_f32 v[110:111], v[110:111], v[206:207]
	v_exp_f32_e32 v230, v230
	v_pk_mul_f32 v[104:105], v[104:105], v[208:209]
	v_exp_f32_e32 v231, v231
	v_pk_mul_f32 v[106:107], v[106:107], v[210:211]
	v_exp_f32_e32 v232, v232
	v_cvt_pk_bf16_f32 v236, v108, v109
	v_exp_f32_e32 v233, v233
	v_cvt_pk_bf16_f32 v237, v110, v111
	v_exp_f32_e32 v234, v234
	v_cvt_pk_bf16_f32 v238, v104, v105
	v_exp_f32_e32 v235, v235
	v_cvt_pk_bf16_f32 v239, v106, v107
	global_store_dwordx4 v[240:241], v[236:239], off
	v_lshl_add_u64 v[240:241], v[240:241], 0, s[100:101]
	v_pk_fma_f32 v[228:229], v[228:229], v[176:177], v[176:177] op_sel_hi:[1,0,0]
	v_pk_fma_f32 v[230:231], v[230:231], v[176:177], v[176:177] op_sel_hi:[1,0,0]
	v_pk_fma_f32 v[232:233], v[232:233], v[176:177], v[176:177] op_sel_hi:[1,0,0]
	v_pk_fma_f32 v[234:235], v[234:235], v[176:177], v[176:177] op_sel_hi:[1,0,0]
	v_rcp_f32_e32 v228, v228
	v_pk_mul_f32 v[204:205], v[76:77], v[194:195] op_sel_hi:[1,0]
	v_rcp_f32_e32 v229, v229
	v_pk_mul_f32 v[206:207], v[78:79], v[194:195] op_sel_hi:[1,0]
	v_rcp_f32_e32 v230, v230
	v_pk_mul_f32 v[208:209], v[72:73], v[194:195] op_sel_hi:[1,0]
	v_rcp_f32_e32 v231, v231
	v_pk_mul_f32 v[210:211], v[74:75], v[194:195] op_sel_hi:[1,0]
	v_rcp_f32_e32 v232, v232
	v_pk_mul_f32 v[76:77], v[76:77], v[68:69]
	v_rcp_f32_e32 v233, v233
	v_pk_mul_f32 v[78:79], v[78:79], v[70:71]
	v_rcp_f32_e32 v234, v234
	v_pk_mul_f32 v[72:73], v[72:73], v[64:65]
	v_rcp_f32_e32 v235, v235
	v_pk_mul_f32 v[74:75], v[74:75], v[66:67]
	v_exp_f32_e32 v204, v204
	v_pk_mul_f32 v[92:93], v[92:93], v[228:229]
	v_exp_f32_e32 v205, v205
	v_pk_mul_f32 v[94:95], v[94:95], v[230:231]
	v_exp_f32_e32 v206, v206
	v_pk_mul_f32 v[88:89], v[88:89], v[232:233]
; __device__ __forceinline__ unsigned pk2(float lo, float hi) { f32x2_t v = {lo, hi}; bf16x2_t b = __builtin_convertvector(v, bf16x2_t); return __builtin_bit_cast(unsigned, b); }
; __device__ __forceinline__ float sigm(float x) { return frcp(1.f + fexp2(-LOG2E * x)); }
;   __device__ __forceinline__ void operator()(const pg8::f32x4 (&acc)[2][2][4][2], const pg8::Unit& u, int wr, int wc, int fr, int fq) const {
;     ...
;       for (int m = 0; m < 4; ++m) {
;         const float r = rs[m]; float v[8];
; #pragma unroll
;         for (int n = 0; n < 2; ++n)
; #pragma unroll
;           for (int c = 0; c < 4; ++c) { const float g = acc[ai][0][m][n][c] * r, uu = acc[ai][1][m][n][c] * r; v[4 * n + c] = g * sigm(g) * uu; }
;         u32x4 w; w.x = pk2(v[0], v[1]); w.y = pk2(v[2], v[3]); w.z = pk2(v[4], v[5]); w.w = pk2(v[6], v[7]);
;         *(u32x4*)(hbuf + (unsigned)(row0 + ai * 128 + m * 16) * DFF + col0) = w;
;       }
	v_exp_f32_e32 v207, v207
	v_pk_mul_f32 v[90:91], v[90:91], v[234:235]
	v_exp_f32_e32 v208, v208
	v_cvt_pk_bf16_f32 v236, v92, v93
	v_exp_f32_e32 v209, v209
	v_cvt_pk_bf16_f32 v237, v94, v95
	v_exp_f32_e32 v210, v210
	v_cvt_pk_bf16_f32 v238, v88, v89
	v_exp_f32_e32 v211, v211
	v_cvt_pk_bf16_f32 v239, v90, v91
	global_store_dwordx4 v[240:241], v[236:239], off
	v_lshl_add_u64 v[240:241], v[240:241], 0, s[100:101]
	v_pk_fma_f32 v[204:205], v[204:205], v[178:179], v[178:179] op_sel_hi:[1,0,0]
	v_pk_fma_f32 v[206:207], v[206:207], v[178:179], v[178:179] op_sel_hi:[1,0,0]
	v_pk_fma_f32 v[208:209], v[208:209], v[178:179], v[178:179] op_sel_hi:[1,0,0]
	v_pk_fma_f32 v[210:211], v[210:211], v[178:179], v[178:179] op_sel_hi:[1,0,0]
	v_rcp_f32_e32 v204, v204
	v_pk_mul_f32 v[228:229], v[60:61], v[196:197] op_sel_hi:[1,0]
	v_rcp_f32_e32 v205, v205
	v_pk_mul_f32 v[230:231], v[62:63], v[196:197] op_sel_hi:[1,0]
	v_rcp_f32_e32 v206, v206
	v_pk_mul_f32 v[232:233], v[56:57], v[196:197] op_sel_hi:[1,0]
	v_rcp_f32_e32 v207, v207
	v_pk_mul_f32 v[234:235], v[58:59], v[196:197] op_sel_hi:[1,0]
	v_rcp_f32_e32 v208, v208
	v_pk_mul_f32 v[60:61], v[60:61], v[52:53]
	v_rcp_f32_e32 v209, v209
	v_pk_mul_f32 v[62:63], v[62:63], v[54:55]
	v_rcp_f32_e32 v210, v210
	v_pk_mul_f32 v[56:57], v[56:57], v[48:49]
	v_rcp_f32_e32 v211, v211
	v_pk_mul_f32 v[58:59], v[58:59], v[50:51]
	v_exp_f32_e32 v228, v228
	v_pk_mul_f32 v[76:77], v[76:77], v[204:205]
	v_exp_f32_e32 v229, v229
	v_pk_mul_f32 v[78:79], v[78:79], v[206:207]
	v_exp_f32_e32 v230, v230
	v_pk_mul_f32 v[72:73], v[72:73], v[208:209]
	v_exp_f32_e32 v231, v231
	v_pk_mul_f32 v[74:75], v[74:75], v[210:211]
	v_exp_f32_e32 v232, v232
	v_cvt_pk_bf16_f32 v236, v76, v77
	v_exp_f32_e32 v233, v233
	v_cvt_pk_bf16_f32 v237, v78, v79
	v_exp_f32_e32 v234, v234
	v_cvt_pk_bf16_f32 v238, v72, v73
	v_exp_f32_e32 v235, v235
	v_cvt_pk_bf16_f32 v239, v74, v75
	global_store_dwordx4 v[240:241], v[236:239], off
	v_pk_fma_f32 v[228:229], v[228:229], v[180:181], v[180:181] op_sel_hi:[1,0,0]
	v_pk_fma_f32 v[230:231], v[230:231], v[180:181], v[180:181] op_sel_hi:[1,0,0]
	v_pk_fma_f32 v[232:233], v[232:233], v[180:181], v[180:181] op_sel_hi:[1,0,0]
	v_pk_fma_f32 v[234:235], v[234:235], v[180:181], v[180:181] op_sel_hi:[1,0,0]
	v_rcp_f32_e32 v228, v228
	v_pk_mul_f32 v[204:205], v[44:45], v[198:199] op_sel_hi:[1,0]
	v_rcp_f32_e32 v229, v229
	v_pk_mul_f32 v[206:207], v[46:47], v[198:199] op_sel_hi:[1,0]
	v_rcp_f32_e32 v230, v230
	v_pk_mul_f32 v[208:209], v[40:41], v[198:199] op_sel_hi:[1,0]
	v_rcp_f32_e32 v231, v231
	v_pk_mul_f32 v[210:211], v[42:43], v[198:199] op_sel_hi:[1,0]
	v_rcp_f32_e32 v232, v232
	v_pk_mul_f32 v[44:45], v[44:45], v[36:37]
	v_rcp_f32_e32 v233, v233
	v_pk_mul_f32 v[46:47], v[46:47], v[38:39]
	v_rcp_f32_e32 v234, v234
	v_pk_mul_f32 v[40:41], v[40:41], v[32:33]
	v_rcp_f32_e32 v235, v235
	v_pk_mul_f32 v[42:43], v[42:43], v[34:35]
	v_exp_f32_e32 v204, v204
	v_pk_mul_f32 v[60:61], v[60:61], v[228:229]
	v_exp_f32_e32 v205, v205
	v_pk_mul_f32 v[62:63], v[62:63], v[230:231]
	v_exp_f32_e32 v206, v206
	v_pk_mul_f32 v[56:57], v[56:57], v[232:233]
	v_exp_f32_e32 v207, v207
	v_pk_mul_f32 v[58:59], v[58:59], v[234:235]
	v_exp_f32_e32 v208, v208
	v_cvt_pk_bf16_f32 v236, v60, v61
	v_exp_f32_e32 v209, v209
	v_cvt_pk_bf16_f32 v237, v62, v63
	v_exp_f32_e32 v210, v210
	v_cvt_pk_bf16_f32 v238, v56, v57
	v_exp_f32_e32 v211, v211
	v_cvt_pk_bf16_f32 v239, v58, v59
	global_store_dwordx4 v[242:243], v[236:239], off
	v_lshl_add_u64 v[242:243], v[242:243], 0, s[100:101]
	v_pk_fma_f32 v[204:205], v[204:205], v[182:183], v[182:183] op_sel_hi:[1,0,0]
	v_pk_fma_f32 v[206:207], v[206:207], v[182:183], v[182:183] op_sel_hi:[1,0,0]
	v_pk_fma_f32 v[208:209], v[208:209], v[182:183], v[182:183] op_sel_hi:[1,0,0]
	v_pk_fma_f32 v[210:211], v[210:211], v[182:183], v[182:183] op_sel_hi:[1,0,0]
	v_rcp_f32_e32 v204, v204
; __device__ __forceinline__ unsigned pk2(float lo, float hi) { f32x2_t v = {lo, hi}; bf16x2_t b = __builtin_convertvector(v, bf16x2_t); return __builtin_bit_cast(unsigned, b); }
; __device__ __forceinline__ float sigm(float x) { return frcp(1.f + fexp2(-LOG2E * x)); }
; #define PG8_BAR __builtin_amdgcn_s_barrier()
; template <class Epi, class Sched, bool ALIGN_EPI = false, bool SP2 = false, bool F16 = false, bool TOKPERM = false>
; __device__ __forceinline__ void gemm_phase(PG8_LAS unsigned char* lds, const Gemm g, const Sched& S, const Epi& E, int wv) {
;     ...
;         if constexpr (ALIGN_EPI) { if (wr == 0) PG8_BAR; }
;         if constexpr (!Epi::AFTER_DRAIN) { E(acc, cur, wr, wc, fr, fq); S.done(cur); }
;         if (!has_next) break;
; #pragma unroll
;         for (int a = 0; a < 2; ++a)
; #pragma unroll
;             for (int b = 0; b < 2; ++b)
; #pragma unroll
;                 for (int m = 0; m < 4; ++m)
; #pragma unroll
;                     for (int n = 0; n < 2; ++n) acc[a][b][m][n] = (f32x4){0.f, 0.f, 0.f, 0.f};
;         cur = nxt; cA = nA; cB = nB; ++ui;
;         if constexpr (ALIGN_EPI) { if (wr == 1) PG8_BAR; }
;   __device__ __forceinline__ void operator()(const pg8::f32x4 (&acc)[2][2][4][2], const pg8::Unit& u, int wr, int wc, int fr, int fq) const {
;     ...
;       for (int m = 0; m < 4; ++m) {
;         const float r = rs[m]; float v[8];
; #pragma unroll
;         for (int n = 0; n < 2; ++n)
; #pragma unroll
;           for (int c = 0; c < 4; ++c) { const float g = acc[ai][0][m][n][c] * r, uu = acc[ai][1][m][n][c] * r; v[4 * n + c] = g * sigm(g) * uu; }
;         u32x4 w; w.x = pk2(v[0], v[1]); w.y = pk2(v[2], v[3]); w.z = pk2(v[4], v[5]); w.w = pk2(v[6], v[7]);
;         *(u32x4*)(hbuf + (unsigned)(row0 + ai * 128 + m * 16) * DFF + col0) = w;
;       }
	v_pk_mul_f32 v[228:229], v[28:29], v[200:201] op_sel_hi:[1,0]
	v_rcp_f32_e32 v205, v205
	v_pk_mul_f32 v[230:231], v[30:31], v[200:201] op_sel_hi:[1,0]
	v_rcp_f32_e32 v206, v206
	v_pk_mul_f32 v[232:233], v[24:25], v[200:201] op_sel_hi:[1,0]
	v_rcp_f32_e32 v207, v207
	v_pk_mul_f32 v[234:235], v[26:27], v[200:201] op_sel_hi:[1,0]
	v_rcp_f32_e32 v208, v208
	v_pk_mul_f32 v[28:29], v[28:29], v[20:21]
	v_rcp_f32_e32 v209, v209
	v_pk_mul_f32 v[30:31], v[30:31], v[22:23]
	v_rcp_f32_e32 v210, v210
	v_pk_mul_f32 v[24:25], v[24:25], v[16:17]
	v_rcp_f32_e32 v211, v211
	v_pk_mul_f32 v[26:27], v[26:27], v[18:19]
	v_exp_f32_e32 v228, v228
	v_pk_mul_f32 v[44:45], v[44:45], v[204:205]
	v_exp_f32_e32 v229, v229
	v_pk_mul_f32 v[46:47], v[46:47], v[206:207]
	v_exp_f32_e32 v230, v230
	v_pk_mul_f32 v[40:41], v[40:41], v[208:209]
	v_exp_f32_e32 v231, v231
	v_pk_mul_f32 v[42:43], v[42:43], v[210:211]
	v_exp_f32_e32 v232, v232
	v_cvt_pk_bf16_f32 v236, v44, v45
	v_exp_f32_e32 v233, v233
	v_cvt_pk_bf16_f32 v237, v46, v47
	v_exp_f32_e32 v234, v234
	v_cvt_pk_bf16_f32 v238, v40, v41
	v_exp_f32_e32 v235, v235
	v_cvt_pk_bf16_f32 v239, v42, v43
	global_store_dwordx4 v[242:243], v[236:239], off
	v_lshl_add_u64 v[242:243], v[242:243], 0, s[100:101]
	v_pk_fma_f32 v[228:229], v[228:229], v[184:185], v[184:185] op_sel_hi:[1,0,0]
	v_pk_fma_f32 v[230:231], v[230:231], v[184:185], v[184:185] op_sel_hi:[1,0,0]
	v_pk_fma_f32 v[232:233], v[232:233], v[184:185], v[184:185] op_sel_hi:[1,0,0]
	v_pk_fma_f32 v[234:235], v[234:235], v[184:185], v[184:185] op_sel_hi:[1,0,0]
	v_rcp_f32_e32 v228, v228
	v_pk_mul_f32 v[204:205], v[12:13], v[202:203] op_sel_hi:[1,0]
	v_rcp_f32_e32 v229, v229
	v_pk_mul_f32 v[206:207], v[14:15], v[202:203] op_sel_hi:[1,0]
	v_rcp_f32_e32 v230, v230
	v_pk_mul_f32 v[208:209], v[8:9], v[202:203] op_sel_hi:[1,0]
	v_rcp_f32_e32 v231, v231
	v_pk_mul_f32 v[210:211], v[10:11], v[202:203] op_sel_hi:[1,0]
	v_rcp_f32_e32 v232, v232
	v_pk_mul_f32 v[12:13], v[12:13], v[4:5]
	v_rcp_f32_e32 v233, v233
	v_pk_mul_f32 v[14:15], v[14:15], v[6:7]
	v_rcp_f32_e32 v234, v234
	v_pk_mul_f32 v[8:9], v[8:9], v[0:1]
	v_rcp_f32_e32 v235, v235
	v_pk_mul_f32 v[10:11], v[10:11], v[2:3]
	v_exp_f32_e32 v204, v204
	v_pk_mul_f32 v[28:29], v[28:29], v[228:229]
	v_exp_f32_e32 v205, v205
	v_pk_mul_f32 v[30:31], v[30:31], v[230:231]
	v_exp_f32_e32 v206, v206
	v_pk_mul_f32 v[24:25], v[24:25], v[232:233]
	v_exp_f32_e32 v207, v207
	v_pk_mul_f32 v[26:27], v[26:27], v[234:235]
	v_exp_f32_e32 v208, v208
	v_cvt_pk_bf16_f32 v236, v28, v29
	v_exp_f32_e32 v209, v209
	v_cvt_pk_bf16_f32 v237, v30, v31
	v_exp_f32_e32 v210, v210
	v_cvt_pk_bf16_f32 v238, v24, v25
	v_exp_f32_e32 v211, v211
	v_cvt_pk_bf16_f32 v239, v26, v27
	global_store_dwordx4 v[242:243], v[236:239], off
	v_lshl_add_u64 v[242:243], v[242:243], 0, s[100:101]
	v_pk_fma_f32 v[204:205], v[204:205], v[186:187], v[186:187] op_sel_hi:[1,0,0]
	v_pk_fma_f32 v[206:207], v[206:207], v[186:187], v[186:187] op_sel_hi:[1,0,0]
	v_pk_fma_f32 v[208:209], v[208:209], v[186:187], v[186:187] op_sel_hi:[1,0,0]
	v_pk_fma_f32 v[210:211], v[210:211], v[186:187], v[186:187] op_sel_hi:[1,0,0]
	v_rcp_f32_e32 v204, v204
	v_rcp_f32_e32 v205, v205
	v_rcp_f32_e32 v206, v206
	v_rcp_f32_e32 v207, v207
	v_rcp_f32_e32 v208, v208
	v_rcp_f32_e32 v209, v209
	v_rcp_f32_e32 v210, v210
	v_rcp_f32_e32 v211, v211
	v_pk_mul_f32 v[12:13], v[12:13], v[204:205]
	v_pk_mul_f32 v[14:15], v[14:15], v[206:207]
	v_pk_mul_f32 v[8:9], v[8:9], v[208:209]
	v_pk_mul_f32 v[10:11], v[10:11], v[210:211]
	v_cvt_pk_bf16_f32 v236, v12, v13
	v_cvt_pk_bf16_f32 v237, v14, v15
	v_cvt_pk_bf16_f32 v238, v8, v9
	v_cvt_pk_bf16_f32 v239, v10, v11
	global_store_dwordx4 v[242:243], v[236:239], off
	s_andn2_b64 vcc, exec, s[2:3]
	s_mov_b64 s[2:3], -1
	s_cbranch_vccnz .LBB0_177
	s_andn2_b64 vcc, exec, s[10:11]
	s_cbranch_vccnz .LBB0_176
	s_barrier
	s_branch .LBB0_176

; __device__ __forceinline__ unsigned pk2(float lo, float hi) { f32x2_t v = {lo, hi}; bf16x2_t b = __builtin_convertvector(v, bf16x2_t); return __builtin_bit_cast(unsigned, b); }
; __device__ __forceinline__ float sigm(float x) { return frcp(1.f + fexp2(-LOG2E * x)); }
;   __device__ __forceinline__ void operator()(const pg8::f32x4 (&acc)[2][2][4][2], const pg8::Unit& u, int wr, int wc, int fr, int fq) const {
;     int z; asm volatile("v_mov_b32 %0, 0" : "=v"(z));
;     const int row0 = u.pm * 256 + wr * 64 + fr + z, col0 = u.pn * 128 + wc * 32 + 8 * fq + z;
; #pragma unroll
;     for (int ai = 0; ai < 2; ++ai) {
;       float rs[4];
; #pragma unroll
;       for (int m = 0; m < 4; ++m) { const f32x4 a = *(const f32x4*)(ssq + (unsigned)(row0 + ai * 128 + m * 16) * 16 + 4 * fq); rs[m] = (a[0] + a[1]) + (a[2] + a[3]); }
; #pragma unroll
;       for (int m = 0; m < 4; ++m) { float v = rs[m]; v += __shfl_xor(v, 16); v += __shfl_xor(v, 32); rs[m] = rsqrtf(v * (1.f / 1024.f) + EPS); }
; #pragma unroll
;       for (int m = 0; m < 4; ++m) {
;         const float r = rs[m]; float v[8];
; #pragma unroll
;         for (int n = 0; n < 2; ++n)
; #pragma unroll
;           for (int c = 0; c < 4; ++c) { const float g = acc[ai][0][m][n][c] * r, uu = acc[ai][1][m][n][c] * r; v[4 * n + c] = g * sigm(g) * uu; }
;         u32x4 w; w.x = pk2(v[0], v[1]); w.y = pk2(v[2], v[3]); w.z = pk2(v[4], v[5]); w.w = pk2(v[6], v[7]);
;         *(u32x4*)(hbuf + (unsigned)(row0 + ai * 128 + m * 16) * DFF + col0) = w;
;       }
;       asm volatile("" ::: "memory");
;     }
;   }
.Lgu_768_havew:
	v_lshl_add_u64 v[242:243], v[240:241], 0, s[100:101]
	s_mov_b32 s100, 0x16000
	v_rsq_f32_e32 v188, v172
	v_rsq_f32_e32 v190, v174
	v_rsq_f32_e32 v192, v176
	v_rsq_f32_e32 v194, v178
	v_rsq_f32_e32 v196, v180
	v_rsq_f32_e32 v198, v182
	v_rsq_f32_e32 v200, v184
	v_rsq_f32_e32 v202, v186
	v_mul_f32_e32 v188, 0xbfb8aa3b, v188
	v_mul_f32_e32 v190, 0xbfb8aa3b, v190
	v_mul_f32_e32 v192, 0xbfb8aa3b, v192
	v_mul_f32_e32 v194, 0xbfb8aa3b, v194
	v_mul_f32_e32 v196, 0xbfb8aa3b, v196
	v_mul_f32_e32 v198, 0xbfb8aa3b, v198
	v_mul_f32_e32 v200, 0xbfb8aa3b, v200
	v_mul_f32_e32 v202, 0xbfb8aa3b, v202
	v_pk_mul_f32 v[228:229], v[124:125], v[188:189] op_sel_hi:[1,0]
	v_pk_mul_f32 v[230:231], v[126:127], v[188:189] op_sel_hi:[1,0]
	v_pk_mul_f32 v[232:233], v[116:117], v[188:189] op_sel_hi:[1,0]
	v_pk_mul_f32 v[234:235], v[118:119], v[188:189] op_sel_hi:[1,0]
	v_exp_f32_e32 v228, v228
	v_exp_f32_e32 v229, v229
	v_pk_mul_f32 v[124:125], v[124:125], v[120:121]
	v_exp_f32_e32 v230, v230
	v_exp_f32_e32 v231, v231
	v_pk_mul_f32 v[126:127], v[126:127], v[122:123]
	v_exp_f32_e32 v232, v232
	v_exp_f32_e32 v233, v233
	v_pk_mul_f32 v[116:117], v[116:117], v[112:113]
	v_exp_f32_e32 v234, v234
	v_exp_f32_e32 v235, v235
	v_pk_mul_f32 v[118:119], v[118:119], v[114:115]
	v_pk_fma_f32 v[228:229], v[228:229], v[172:173], v[172:173] op_sel_hi:[1,0,0]
	v_pk_fma_f32 v[230:231], v[230:231], v[172:173], v[172:173] op_sel_hi:[1,0,0]
	v_pk_fma_f32 v[232:233], v[232:233], v[172:173], v[172:173] op_sel_hi:[1,0,0]
	v_pk_fma_f32 v[234:235], v[234:235], v[172:173], v[172:173] op_sel_hi:[1,0,0]
	v_rcp_f32_e32 v228, v228
	v_pk_mul_f32 v[204:205], v[108:109], v[190:191] op_sel_hi:[1,0]
	v_rcp_f32_e32 v229, v229
	v_pk_mul_f32 v[206:207], v[110:111], v[190:191] op_sel_hi:[1,0]
	v_rcp_f32_e32 v230, v230
	v_pk_mul_f32 v[208:209], v[104:105], v[190:191] op_sel_hi:[1,0]
	v_rcp_f32_e32 v231, v231
	v_pk_mul_f32 v[210:211], v[106:107], v[190:191] op_sel_hi:[1,0]
	v_rcp_f32_e32 v232, v232
	v_pk_mul_f32 v[108:109], v[108:109], v[100:101]
	v_rcp_f32_e32 v233, v233
	v_pk_mul_f32 v[110:111], v[110:111], v[102:103]
	v_rcp_f32_e32 v234, v234
	v_pk_mul_f32 v[104:105], v[104:105], v[96:97]
	v_rcp_f32_e32 v235, v235
	v_pk_mul_f32 v[106:107], v[106:107], v[98:99]
	v_exp_f32_e32 v204, v204
	v_pk_mul_f32 v[124:125], v[124:125], v[228:229]
	v_exp_f32_e32 v205, v205
	v_pk_mul_f32 v[126:127], v[126:127], v[230:231]
	v_exp_f32_e32 v206, v206
	v_pk_mul_f32 v[116:117], v[116:117], v[232:233]
	v_exp_f32_e32 v207, v207
	v_pk_mul_f32 v[118:119], v[118:119], v[234:235]
	v_exp_f32_e32 v208, v208
	v_cvt_pk_bf16_f32 v236, v124, v125
	v_exp_f32_e32 v209, v209
	v_cvt_pk_bf16_f32 v237, v126, v127
	v_exp_f32_e32 v210, v210
	v_cvt_pk_bf16_f32 v238, v116, v117
	v_exp_f32_e32 v211, v211
	v_cvt_pk_bf16_f32 v239, v118, v119
	global_store_dwordx4 v[240:241], v[236:239], off
	v_lshl_add_u64 v[240:241], v[240:241], 0, s[100:101]
	v_pk_fma_f32 v[204:205], v[204:205], v[174:175], v[174:175] op_sel_hi:[1,0,0]
	v_pk_fma_f32 v[206:207], v[206:207], v[174:175], v[174:175] op_sel_hi:[1,0,0]
	v_pk_fma_f32 v[208:209], v[208:209], v[174:175], v[174:175] op_sel_hi:[1,0,0]
	v_pk_fma_f32 v[210:211], v[210:211], v[174:175], v[174:175] op_sel_hi:[1,0,0]
	v_rcp_f32_e32 v204, v204
	v_pk_mul_f32 v[228:229], v[92:93], v[192:193] op_sel_hi:[1,0]
	v_rcp_f32_e32 v205, v205
	v_pk_mul_f32 v[230:231], v[94:95], v[192:193] op_sel_hi:[1,0]
	v_rcp_f32_e32 v206, v206
	v_pk_mul_f32 v[232:233], v[88:89], v[192:193] op_sel_hi:[1,0]
	v_rcp_f32_e32 v207, v207
	v_pk_mul_f32 v[234:235], v[90:91], v[192:193] op_sel_hi:[1,0]
	v_rcp_f32_e32 v208, v208
	v_pk_mul_f32 v[92:93], v[92:93], v[84:85]
	v_rcp_f32_e32 v209, v209
	v_pk_mul_f32 v[94:95], v[94:95], v[86:87]
	v_rcp_f32_e32 v210, v210
	v_pk_mul_f32 v[88:89], v[88:89], v[80:81]
	v_rcp_f32_e32 v211, v211
	v_pk_mul_f32 v[90:91], v[90:91], v[82:83]
	v_exp_f32_e32 v228, v228
	v_pk_mul_f32 v[108:109], v[108:109], v[204:205]
	v_exp_f32_e32 v229, v229
	v_pk_mul_f32 v[110:111], v[110:111], v[206:207]
	v_exp_f32_e32 v230, v230
	v_pk_mul_f32 v[104:105], v[104:105], v[208:209]
	v_exp_f32_e32 v231, v231
	v_pk_mul_f32 v[106:107], v[106:107], v[210:211]
	v_exp_f32_e32 v232, v232
	v_cvt_pk_bf16_f32 v236, v108, v109
	v_exp_f32_e32 v233, v233
	v_cvt_pk_bf16_f32 v237, v110, v111
	v_exp_f32_e32 v234, v234
	v_cvt_pk_bf16_f32 v238, v104, v105
	v_exp_f32_e32 v235, v235
	v_cvt_pk_bf16_f32 v239, v106, v107
	global_store_dwordx4 v[240:241], v[236:239], off
	v_lshl_add_u64 v[240:241], v[240:241], 0, s[100:101]
	v_pk_fma_f32 v[228:229], v[228:229], v[176:177], v[176:177] op_sel_hi:[1,0,0]
	v_pk_fma_f32 v[230:231], v[230:231], v[176:177], v[176:177] op_sel_hi:[1,0,0]
	v_pk_fma_f32 v[232:233], v[232:233], v[176:177], v[176:177] op_sel_hi:[1,0,0]
	v_pk_fma_f32 v[234:235], v[234:235], v[176:177], v[176:177] op_sel_hi:[1,0,0]
	v_rcp_f32_e32 v228, v228
	v_pk_mul_f32 v[204:205], v[76:77], v[194:195] op_sel_hi:[1,0]
	v_rcp_f32_e32 v229, v229
	v_pk_mul_f32 v[206:207], v[78:79], v[194:195] op_sel_hi:[1,0]
	v_rcp_f32_e32 v230, v230
	v_pk_mul_f32 v[208:209], v[72:73], v[194:195] op_sel_hi:[1,0]
	v_rcp_f32_e32 v231, v231
	v_pk_mul_f32 v[210:211], v[74:75], v[194:195] op_sel_hi:[1,0]
	v_rcp_f32_e32 v232, v232
	v_pk_mul_f32 v[76:77], v[76:77], v[68:69]
	v_rcp_f32_e32 v233, v233
	v_pk_mul_f32 v[78:79], v[78:79], v[70:71]
	v_rcp_f32_e32 v234, v234
	v_pk_mul_f32 v[72:73], v[72:73], v[64:65]
	v_rcp_f32_e32 v235, v235
	v_pk_mul_f32 v[74:75], v[74:75], v[66:67]
	v_exp_f32_e32 v204, v204
	v_pk_mul_f32 v[92:93], v[92:93], v[228:229]
	v_exp_f32_e32 v205, v205
	v_pk_mul_f32 v[94:95], v[94:95], v[230:231]
	v_exp_f32_e32 v206, v206
	v_pk_mul_f32 v[88:89], v[88:89], v[232:233]
; __device__ __forceinline__ unsigned pk2(float lo, float hi) { f32x2_t v = {lo, hi}; bf16x2_t b = __builtin_convertvector(v, bf16x2_t); return __builtin_bit_cast(unsigned, b); }
; __device__ __forceinline__ float sigm(float x) { return frcp(1.f + fexp2(-LOG2E * x)); }
;   __device__ __forceinline__ void operator()(const pg8::f32x4 (&acc)[2][2][4][2], const pg8::Unit& u, int wr, int wc, int fr, int fq) const {
;     ...
;       for (int m = 0; m < 4; ++m) {
;         const float r = rs[m]; float v[8];
; #pragma unroll
;         for (int n = 0; n < 2; ++n)
; #pragma unroll
;           for (int c = 0; c < 4; ++c) { const float g = acc[ai][0][m][n][c] * r, uu = acc[ai][1][m][n][c] * r; v[4 * n + c] = g * sigm(g) * uu; }
;         u32x4 w; w.x = pk2(v[0], v[1]); w.y = pk2(v[2], v[3]); w.z = pk2(v[4], v[5]); w.w = pk2(v[6], v[7]);
;         *(u32x4*)(hbuf + (unsigned)(row0 + ai * 128 + m * 16) * DFF + col0) = w;
	v_exp_f32_e32 v207, v207
	v_pk_mul_f32 v[90:91], v[90:91], v[234:235]
	v_exp_f32_e32 v208, v208
	v_cvt_pk_bf16_f32 v236, v92, v93
	v_exp_f32_e32 v209, v209
	v_cvt_pk_bf16_f32 v237, v94, v95
	v_exp_f32_e32 v210, v210
	v_cvt_pk_bf16_f32 v238, v88, v89
	v_exp_f32_e32 v211, v211
	v_cvt_pk_bf16_f32 v239, v90, v91
	global_store_dwordx4 v[240:241], v[236:239], off
	v_lshl_add_u64 v[240:241], v[240:241], 0, s[100:101]
	v_pk_fma_f32 v[204:205], v[204:205], v[178:179], v[178:179] op_sel_hi:[1,0,0]
	v_pk_fma_f32 v[206:207], v[206:207], v[178:179], v[178:179] op_sel_hi:[1,0,0]
	v_pk_fma_f32 v[208:209], v[208:209], v[178:179], v[178:179] op_sel_hi:[1,0,0]
	v_pk_fma_f32 v[210:211], v[210:211], v[178:179], v[178:179] op_sel_hi:[1,0,0]
	v_rcp_f32_e32 v204, v204
	v_pk_mul_f32 v[228:229], v[60:61], v[196:197] op_sel_hi:[1,0]
	v_rcp_f32_e32 v205, v205
	v_pk_mul_f32 v[230:231], v[62:63], v[196:197] op_sel_hi:[1,0]
	v_rcp_f32_e32 v206, v206
	v_pk_mul_f32 v[232:233], v[56:57], v[196:197] op_sel_hi:[1,0]
	v_rcp_f32_e32 v207, v207
	v_pk_mul_f32 v[234:235], v[58:59], v[196:197] op_sel_hi:[1,0]
	v_rcp_f32_e32 v208, v208
	v_pk_mul_f32 v[60:61], v[60:61], v[52:53]
	v_rcp_f32_e32 v209, v209
	v_pk_mul_f32 v[62:63], v[62:63], v[54:55]
	v_rcp_f32_e32 v210, v210
	v_pk_mul_f32 v[56:57], v[56:57], v[48:49]
	v_rcp_f32_e32 v211, v211
	v_pk_mul_f32 v[58:59], v[58:59], v[50:51]
	v_exp_f32_e32 v228, v228
	v_pk_mul_f32 v[76:77], v[76:77], v[204:205]
	v_exp_f32_e32 v229, v229
	v_pk_mul_f32 v[78:79], v[78:79], v[206:207]
	v_exp_f32_e32 v230, v230
	v_pk_mul_f32 v[72:73], v[72:73], v[208:209]
	v_exp_f32_e32 v231, v231
	v_pk_mul_f32 v[74:75], v[74:75], v[210:211]
	v_exp_f32_e32 v232, v232
	v_cvt_pk_bf16_f32 v236, v76, v77
	v_exp_f32_e32 v233, v233
	v_cvt_pk_bf16_f32 v237, v78, v79
	v_exp_f32_e32 v234, v234
	v_cvt_pk_bf16_f32 v238, v72, v73
	v_exp_f32_e32 v235, v235
	v_cvt_pk_bf16_f32 v239, v74, v75
	global_store_dwordx4 v[240:241], v[236:239], off
	v_pk_fma_f32 v[228:229], v[228:229], v[180:181], v[180:181] op_sel_hi:[1,0,0]
	v_pk_fma_f32 v[230:231], v[230:231], v[180:181], v[180:181] op_sel_hi:[1,0,0]
	v_pk_fma_f32 v[232:233], v[232:233], v[180:181], v[180:181] op_sel_hi:[1,0,0]
	v_pk_fma_f32 v[234:235], v[234:235], v[180:181], v[180:181] op_sel_hi:[1,0,0]
	v_rcp_f32_e32 v228, v228
	v_pk_mul_f32 v[204:205], v[44:45], v[198:199] op_sel_hi:[1,0]
	v_rcp_f32_e32 v229, v229
	v_pk_mul_f32 v[206:207], v[46:47], v[198:199] op_sel_hi:[1,0]
	v_rcp_f32_e32 v230, v230
	v_pk_mul_f32 v[208:209], v[40:41], v[198:199] op_sel_hi:[1,0]
	v_rcp_f32_e32 v231, v231
	v_pk_mul_f32 v[210:211], v[42:43], v[198:199] op_sel_hi:[1,0]
	v_rcp_f32_e32 v232, v232
	v_pk_mul_f32 v[44:45], v[44:45], v[36:37]
	v_rcp_f32_e32 v233, v233
	v_pk_mul_f32 v[46:47], v[46:47], v[38:39]
	v_rcp_f32_e32 v234, v234
	v_pk_mul_f32 v[40:41], v[40:41], v[32:33]
	v_rcp_f32_e32 v235, v235
	v_pk_mul_f32 v[42:43], v[42:43], v[34:35]
	v_exp_f32_e32 v204, v204
	v_pk_mul_f32 v[60:61], v[60:61], v[228:229]
	v_exp_f32_e32 v205, v205
	v_pk_mul_f32 v[62:63], v[62:63], v[230:231]
	v_exp_f32_e32 v206, v206
	v_pk_mul_f32 v[56:57], v[56:57], v[232:233]
	v_exp_f32_e32 v207, v207
	v_pk_mul_f32 v[58:59], v[58:59], v[234:235]
	v_exp_f32_e32 v208, v208
	v_cvt_pk_bf16_f32 v236, v60, v61
	v_exp_f32_e32 v209, v209
	v_cvt_pk_bf16_f32 v237, v62, v63
	v_exp_f32_e32 v210, v210
	v_cvt_pk_bf16_f32 v238, v56, v57
	v_exp_f32_e32 v211, v211
	v_cvt_pk_bf16_f32 v239, v58, v59
	global_store_dwordx4 v[242:243], v[236:239], off
	v_lshl_add_u64 v[242:243], v[242:243], 0, s[100:101]
	v_pk_fma_f32 v[204:205], v[204:205], v[182:183], v[182:183] op_sel_hi:[1,0,0]
	v_pk_fma_f32 v[206:207], v[206:207], v[182:183], v[182:183] op_sel_hi:[1,0,0]
	v_pk_fma_f32 v[208:209], v[208:209], v[182:183], v[182:183] op_sel_hi:[1,0,0]
	v_pk_fma_f32 v[210:211], v[210:211], v[182:183], v[182:183] op_sel_hi:[1,0,0]
	v_rcp_f32_e32 v204, v204
; __device__ __forceinline__ unsigned pk2(float lo, float hi) { f32x2_t v = {lo, hi}; bf16x2_t b = __builtin_convertvector(v, bf16x2_t); return __builtin_bit_cast(unsigned, b); }
; __device__ __forceinline__ float sigm(float x) { return frcp(1.f + fexp2(-LOG2E * x)); }
; #define PG8_BAR __builtin_amdgcn_s_barrier()
; template <class Epi, class Sched, bool ALIGN_EPI = false, bool SP2 = false, bool F16 = false, bool TOKPERM = false>
; __device__ __forceinline__ void gemm_phase(PG8_LAS unsigned char* lds, const Gemm g, const Sched& S, const Epi& E, int wv) {
;     ...
;         if constexpr (ALIGN_EPI) { if (wr == 0) PG8_BAR; }
;         if constexpr (!Epi::AFTER_DRAIN) { E(acc, cur, wr, wc, fr, fq); S.done(cur); }
;         if (!has_next) break;
; #pragma unroll
;         for (int a = 0; a < 2; ++a)
; #pragma unroll
;             for (int b = 0; b < 2; ++b)
; #pragma unroll
;                 for (int m = 0; m < 4; ++m)
; #pragma unroll
;                     for (int n = 0; n < 2; ++n) acc[a][b][m][n] = (f32x4){0.f, 0.f, 0.f, 0.f};
;         cur = nxt; cA = nA; cB = nB; ++ui;
;         if constexpr (ALIGN_EPI) { if (wr == 1) PG8_BAR; }
;   __device__ __forceinline__ void operator()(const pg8::f32x4 (&acc)[2][2][4][2], const pg8::Unit& u, int wr, int wc, int fr, int fq) const {
;     ...
;       for (int m = 0; m < 4; ++m) {
;         const float r = rs[m]; float v[8];
; #pragma unroll
;         for (int n = 0; n < 2; ++n)
; #pragma unroll
;           for (int c = 0; c < 4; ++c) { const float g = acc[ai][0][m][n][c] * r, uu = acc[ai][1][m][n][c] * r; v[4 * n + c] = g * sigm(g) * uu; }
;         u32x4 w; w.x = pk2(v[0], v[1]); w.y = pk2(v[2], v[3]); w.z = pk2(v[4], v[5]); w.w = pk2(v[6], v[7]);
;         *(u32x4*)(hbuf + (unsigned)(row0 + ai * 128 + m * 16) * DFF + col0) = w;
	v_pk_mul_f32 v[228:229], v[28:29], v[200:201] op_sel_hi:[1,0]
	v_rcp_f32_e32 v205, v205
	v_pk_mul_f32 v[230:231], v[30:31], v[200:201] op_sel_hi:[1,0]
	v_rcp_f32_e32 v206, v206
	v_pk_mul_f32 v[232:233], v[24:25], v[200:201] op_sel_hi:[1,0]
	v_rcp_f32_e32 v207, v207
	v_pk_mul_f32 v[234:235], v[26:27], v[200:201] op_sel_hi:[1,0]
	v_rcp_f32_e32 v208, v208
	v_pk_mul_f32 v[28:29], v[28:29], v[20:21]
	v_rcp_f32_e32 v209, v209
	v_pk_mul_f32 v[30:31], v[30:31], v[22:23]
	v_rcp_f32_e32 v210, v210
	v_pk_mul_f32 v[24:25], v[24:25], v[16:17]
	v_rcp_f32_e32 v211, v211
	v_pk_mul_f32 v[26:27], v[26:27], v[18:19]
	v_exp_f32_e32 v228, v228
	v_pk_mul_f32 v[44:45], v[44:45], v[204:205]
	v_exp_f32_e32 v229, v229
	v_pk_mul_f32 v[46:47], v[46:47], v[206:207]
	v_exp_f32_e32 v230, v230
	v_pk_mul_f32 v[40:41], v[40:41], v[208:209]
	v_exp_f32_e32 v231, v231
	v_pk_mul_f32 v[42:43], v[42:43], v[210:211]
	v_exp_f32_e32 v232, v232
	v_cvt_pk_bf16_f32 v236, v44, v45
	v_exp_f32_e32 v233, v233
	v_cvt_pk_bf16_f32 v237, v46, v47
	v_exp_f32_e32 v234, v234
	v_cvt_pk_bf16_f32 v238, v40, v41
	v_exp_f32_e32 v235, v235
	v_cvt_pk_bf16_f32 v239, v42, v43
	global_store_dwordx4 v[242:243], v[236:239], off
	v_lshl_add_u64 v[242:243], v[242:243], 0, s[100:101]
	v_pk_fma_f32 v[228:229], v[228:229], v[184:185], v[184:185] op_sel_hi:[1,0,0]
	v_pk_fma_f32 v[230:231], v[230:231], v[184:185], v[184:185] op_sel_hi:[1,0,0]
	v_pk_fma_f32 v[232:233], v[232:233], v[184:185], v[184:185] op_sel_hi:[1,0,0]
	v_pk_fma_f32 v[234:235], v[234:235], v[184:185], v[184:185] op_sel_hi:[1,0,0]
	v_rcp_f32_e32 v228, v228
	v_pk_mul_f32 v[204:205], v[12:13], v[202:203] op_sel_hi:[1,0]
	v_rcp_f32_e32 v229, v229
	v_pk_mul_f32 v[206:207], v[14:15], v[202:203] op_sel_hi:[1,0]
	v_rcp_f32_e32 v230, v230
	v_pk_mul_f32 v[208:209], v[8:9], v[202:203] op_sel_hi:[1,0]
	v_rcp_f32_e32 v231, v231
	v_pk_mul_f32 v[210:211], v[10:11], v[202:203] op_sel_hi:[1,0]
	v_rcp_f32_e32 v232, v232
	v_pk_mul_f32 v[12:13], v[12:13], v[4:5]
	v_rcp_f32_e32 v233, v233
	v_pk_mul_f32 v[14:15], v[14:15], v[6:7]
	v_rcp_f32_e32 v234, v234
	v_pk_mul_f32 v[8:9], v[8:9], v[0:1]
	v_rcp_f32_e32 v235, v235
	v_pk_mul_f32 v[10:11], v[10:11], v[2:3]
	v_exp_f32_e32 v204, v204
	v_pk_mul_f32 v[28:29], v[28:29], v[228:229]
	v_exp_f32_e32 v205, v205
	v_pk_mul_f32 v[30:31], v[30:31], v[230:231]
	v_exp_f32_e32 v206, v206
	v_pk_mul_f32 v[24:25], v[24:25], v[232:233]
	v_exp_f32_e32 v207, v207
	v_pk_mul_f32 v[26:27], v[26:27], v[234:235]
	v_exp_f32_e32 v208, v208
	v_cvt_pk_bf16_f32 v236, v28, v29
	v_exp_f32_e32 v209, v209
	v_cvt_pk_bf16_f32 v237, v30, v31
	v_exp_f32_e32 v210, v210
	v_cvt_pk_bf16_f32 v238, v24, v25
	v_exp_f32_e32 v211, v211
	v_cvt_pk_bf16_f32 v239, v26, v27
	global_store_dwordx4 v[242:243], v[236:239], off
	v_lshl_add_u64 v[242:243], v[242:243], 0, s[100:101]
	v_pk_fma_f32 v[204:205], v[204:205], v[186:187], v[186:187] op_sel_hi:[1,0,0]
	v_pk_fma_f32 v[206:207], v[206:207], v[186:187], v[186:187] op_sel_hi:[1,0,0]
	v_pk_fma_f32 v[208:209], v[208:209], v[186:187], v[186:187] op_sel_hi:[1,0,0]
	v_pk_fma_f32 v[210:211], v[210:211], v[186:187], v[186:187] op_sel_hi:[1,0,0]
	v_rcp_f32_e32 v204, v204
	v_rcp_f32_e32 v205, v205
	v_rcp_f32_e32 v206, v206
	v_rcp_f32_e32 v207, v207
	v_rcp_f32_e32 v208, v208
	v_rcp_f32_e32 v209, v209
	v_rcp_f32_e32 v210, v210
	v_rcp_f32_e32 v211, v211
	v_pk_mul_f32 v[12:13], v[12:13], v[204:205]
	v_pk_mul_f32 v[14:15], v[14:15], v[206:207]
	v_pk_mul_f32 v[8:9], v[8:9], v[208:209]
	v_pk_mul_f32 v[10:11], v[10:11], v[210:211]
	v_cvt_pk_bf16_f32 v236, v12, v13
	v_cvt_pk_bf16_f32 v237, v14, v15
	v_cvt_pk_bf16_f32 v238, v8, v9
	v_cvt_pk_bf16_f32 v239, v10, v11
	global_store_dwordx4 v[242:243], v[236:239], off
	s_andn2_b64 vcc, exec, s[6:7]
	s_mov_b64 s[6:7], -1
	s_cbranch_vccnz .LBB0_764
	s_andn2_b64 vcc, exec, s[14:15]
	s_cbranch_vccnz .LBB0_763
	s_barrier
	s_branch .LBB0_763

; __device__ __forceinline__ unsigned pk2(float lo, float hi) { f32x2_t v = {lo, hi}; bf16x2_t b = __builtin_convertvector(v, bf16x2_t); return __builtin_bit_cast(unsigned, b); }
; __device__ __forceinline__ float sigm(float x) { return frcp(1.f + fexp2(-LOG2E * x)); }
;   __device__ __forceinline__ void operator()(const pg8::f32x4 (&acc)[2][2][4][2], const pg8::Unit& u, int wr, int wc, int fr, int fq) const {
;     ...
;     const int row0 = u.pm * 256 + wr * 64 + fr + z, col0 = u.pn * 128 + wc * 32 + 8 * fq + z;
; #pragma unroll
;     for (int ai = 0; ai < 2; ++ai) {
;       float rs[4];
; #pragma unroll
;       for (int m = 0; m < 4; ++m) { const f32x4 a = *(const f32x4*)(ssq + (unsigned)(row0 + ai * 128 + m * 16) * 16 + 4 * fq); rs[m] = (a[0] + a[1]) + (a[2] + a[3]); }
; #pragma unroll
;       for (int m = 0; m < 4; ++m) { float v = rs[m]; v += __shfl_xor(v, 16); v += __shfl_xor(v, 32); rs[m] = rsqrtf(v * (1.f / 1024.f) + EPS); }
; #pragma unroll
;       for (int m = 0; m < 4; ++m) {
;         const float r = rs[m]; float v[8];
; #pragma unroll
;         for (int n = 0; n < 2; ++n)
; #pragma unroll
;           for (int c = 0; c < 4; ++c) { const float g = acc[ai][0][m][n][c] * r, uu = acc[ai][1][m][n][c] * r; v[4 * n + c] = g * sigm(g) * uu; }
;         u32x4 w; w.x = pk2(v[0], v[1]); w.y = pk2(v[2], v[3]); w.z = pk2(v[4], v[5]); w.w = pk2(v[6], v[7]);
;         *(u32x4*)(hbuf + (unsigned)(row0 + ai * 128 + m * 16) * DFF + col0) = w;
.Lgu_1607_havew:
	v_lshl_add_u64 v[242:243], v[240:241], 0, s[100:101]
	s_mov_b32 s100, 0x16000
	v_rsq_f32_e32 v188, v172
	v_rsq_f32_e32 v190, v174
	v_rsq_f32_e32 v192, v176
	v_rsq_f32_e32 v194, v178
	v_rsq_f32_e32 v196, v180
	v_rsq_f32_e32 v198, v182
	v_rsq_f32_e32 v200, v184
	v_rsq_f32_e32 v202, v186
	v_mul_f32_e32 v188, 0xbfb8aa3b, v188
	v_mul_f32_e32 v190, 0xbfb8aa3b, v190
	v_mul_f32_e32 v192, 0xbfb8aa3b, v192
	v_mul_f32_e32 v194, 0xbfb8aa3b, v194
	v_mul_f32_e32 v196, 0xbfb8aa3b, v196
	v_mul_f32_e32 v198, 0xbfb8aa3b, v198
	v_mul_f32_e32 v200, 0xbfb8aa3b, v200
	v_mul_f32_e32 v202, 0xbfb8aa3b, v202
	v_pk_mul_f32 v[228:229], v[124:125], v[188:189] op_sel_hi:[1,0]
	v_pk_mul_f32 v[230:231], v[126:127], v[188:189] op_sel_hi:[1,0]
	v_pk_mul_f32 v[232:233], v[116:117], v[188:189] op_sel_hi:[1,0]
	v_pk_mul_f32 v[234:235], v[118:119], v[188:189] op_sel_hi:[1,0]
	v_exp_f32_e32 v228, v228
	v_exp_f32_e32 v229, v229
	v_pk_mul_f32 v[124:125], v[124:125], v[120:121]
	v_exp_f32_e32 v230, v230
	v_exp_f32_e32 v231, v231
	v_pk_mul_f32 v[126:127], v[126:127], v[122:123]
	v_exp_f32_e32 v232, v232
	v_exp_f32_e32 v233, v233
	v_pk_mul_f32 v[116:117], v[116:117], v[112:113]
	v_exp_f32_e32 v234, v234
	v_exp_f32_e32 v235, v235
	v_pk_mul_f32 v[118:119], v[118:119], v[114:115]
	v_pk_fma_f32 v[228:229], v[228:229], v[172:173], v[172:173] op_sel_hi:[1,0,0]
	v_pk_fma_f32 v[230:231], v[230:231], v[172:173], v[172:173] op_sel_hi:[1,0,0]
	v_pk_fma_f32 v[232:233], v[232:233], v[172:173], v[172:173] op_sel_hi:[1,0,0]
	v_pk_fma_f32 v[234:235], v[234:235], v[172:173], v[172:173] op_sel_hi:[1,0,0]
	v_rcp_f32_e32 v228, v228
	v_pk_mul_f32 v[204:205], v[108:109], v[190:191] op_sel_hi:[1,0]
	v_rcp_f32_e32 v229, v229
	v_pk_mul_f32 v[206:207], v[110:111], v[190:191] op_sel_hi:[1,0]
	v_rcp_f32_e32 v230, v230
	v_pk_mul_f32 v[208:209], v[104:105], v[190:191] op_sel_hi:[1,0]
	v_rcp_f32_e32 v231, v231
	v_pk_mul_f32 v[210:211], v[106:107], v[190:191] op_sel_hi:[1,0]
	v_rcp_f32_e32 v232, v232
	v_pk_mul_f32 v[108:109], v[108:109], v[100:101]
	v_rcp_f32_e32 v233, v233
	v_pk_mul_f32 v[110:111], v[110:111], v[102:103]
	v_rcp_f32_e32 v234, v234
	v_pk_mul_f32 v[104:105], v[104:105], v[96:97]
	v_rcp_f32_e32 v235, v235
	v_pk_mul_f32 v[106:107], v[106:107], v[98:99]
	v_exp_f32_e32 v204, v204
	v_pk_mul_f32 v[124:125], v[124:125], v[228:229]
	v_exp_f32_e32 v205, v205
	v_pk_mul_f32 v[126:127], v[126:127], v[230:231]
	v_exp_f32_e32 v206, v206
	v_pk_mul_f32 v[116:117], v[116:117], v[232:233]
	v_exp_f32_e32 v207, v207
	v_pk_mul_f32 v[118:119], v[118:119], v[234:235]
	v_exp_f32_e32 v208, v208
	v_cvt_pk_bf16_f32 v236, v124, v125
	v_exp_f32_e32 v209, v209
	v_cvt_pk_bf16_f32 v237, v126, v127
	v_exp_f32_e32 v210, v210
	v_cvt_pk_bf16_f32 v238, v116, v117
	v_exp_f32_e32 v211, v211
	v_cvt_pk_bf16_f32 v239, v118, v119
	global_store_dwordx4 v[240:241], v[236:239], off
	v_lshl_add_u64 v[240:241], v[240:241], 0, s[100:101]
	v_pk_fma_f32 v[204:205], v[204:205], v[174:175], v[174:175] op_sel_hi:[1,0,0]
	v_pk_fma_f32 v[206:207], v[206:207], v[174:175], v[174:175] op_sel_hi:[1,0,0]
	v_pk_fma_f32 v[208:209], v[208:209], v[174:175], v[174:175] op_sel_hi:[1,0,0]
	v_pk_fma_f32 v[210:211], v[210:211], v[174:175], v[174:175] op_sel_hi:[1,0,0]
	v_rcp_f32_e32 v204, v204
	v_pk_mul_f32 v[228:229], v[92:93], v[192:193] op_sel_hi:[1,0]
	v_rcp_f32_e32 v205, v205
	v_pk_mul_f32 v[230:231], v[94:95], v[192:193] op_sel_hi:[1,0]
	v_rcp_f32_e32 v206, v206
	v_pk_mul_f32 v[232:233], v[88:89], v[192:193] op_sel_hi:[1,0]
	v_rcp_f32_e32 v207, v207
	v_pk_mul_f32 v[234:235], v[90:91], v[192:193] op_sel_hi:[1,0]
	v_rcp_f32_e32 v208, v208
	v_pk_mul_f32 v[92:93], v[92:93], v[84:85]
	v_rcp_f32_e32 v209, v209
	v_pk_mul_f32 v[94:95], v[94:95], v[86:87]
	v_rcp_f32_e32 v210, v210
	v_pk_mul_f32 v[88:89], v[88:89], v[80:81]
	v_rcp_f32_e32 v211, v211
	v_pk_mul_f32 v[90:91], v[90:91], v[82:83]
	v_exp_f32_e32 v228, v228
	v_pk_mul_f32 v[108:109], v[108:109], v[204:205]
	v_exp_f32_e32 v229, v229
	v_pk_mul_f32 v[110:111], v[110:111], v[206:207]
	v_exp_f32_e32 v230, v230
	v_pk_mul_f32 v[104:105], v[104:105], v[208:209]
	v_exp_f32_e32 v231, v231
	v_pk_mul_f32 v[106:107], v[106:107], v[210:211]
	v_exp_f32_e32 v232, v232
	v_cvt_pk_bf16_f32 v236, v108, v109
	v_exp_f32_e32 v233, v233
	v_cvt_pk_bf16_f32 v237, v110, v111
	v_exp_f32_e32 v234, v234
	v_cvt_pk_bf16_f32 v238, v104, v105
	v_exp_f32_e32 v235, v235
	v_cvt_pk_bf16_f32 v239, v106, v107
	global_store_dwordx4 v[240:241], v[236:239], off
	v_lshl_add_u64 v[240:241], v[240:241], 0, s[100:101]
	v_pk_fma_f32 v[228:229], v[228:229], v[176:177], v[176:177] op_sel_hi:[1,0,0]
	v_pk_fma_f32 v[230:231], v[230:231], v[176:177], v[176:177] op_sel_hi:[1,0,0]
	v_pk_fma_f32 v[232:233], v[232:233], v[176:177], v[176:177] op_sel_hi:[1,0,0]
	v_pk_fma_f32 v[234:235], v[234:235], v[176:177], v[176:177] op_sel_hi:[1,0,0]
	v_rcp_f32_e32 v228, v228
	v_pk_mul_f32 v[204:205], v[76:77], v[194:195] op_sel_hi:[1,0]
	v_rcp_f32_e32 v229, v229
	v_pk_mul_f32 v[206:207], v[78:79], v[194:195] op_sel_hi:[1,0]
	v_rcp_f32_e32 v230, v230
	v_pk_mul_f32 v[208:209], v[72:73], v[194:195] op_sel_hi:[1,0]
	v_rcp_f32_e32 v231, v231
	v_pk_mul_f32 v[210:211], v[74:75], v[194:195] op_sel_hi:[1,0]
	v_rcp_f32_e32 v232, v232
	v_pk_mul_f32 v[76:77], v[76:77], v[68:69]
	v_rcp_f32_e32 v233, v233
	v_pk_mul_f32 v[78:79], v[78:79], v[70:71]
	v_rcp_f32_e32 v234, v234
	v_pk_mul_f32 v[72:73], v[72:73], v[64:65]
	v_rcp_f32_e32 v235, v235
	v_pk_mul_f32 v[74:75], v[74:75], v[66:67]
	v_exp_f32_e32 v204, v204
	v_pk_mul_f32 v[92:93], v[92:93], v[228:229]
	v_exp_f32_e32 v205, v205
	v_pk_mul_f32 v[94:95], v[94:95], v[230:231]
	v_exp_f32_e32 v206, v206
	v_pk_mul_f32 v[88:89], v[88:89], v[232:233]
; __device__ __forceinline__ unsigned pk2(float lo, float hi) { f32x2_t v = {lo, hi}; bf16x2_t b = __builtin_convertvector(v, bf16x2_t); return __builtin_bit_cast(unsigned, b); }
; __device__ __forceinline__ float sigm(float x) { return frcp(1.f + fexp2(-LOG2E * x)); }
;   __device__ __forceinline__ void operator()(const pg8::f32x4 (&acc)[2][2][4][2], const pg8::Unit& u, int wr, int wc, int fr, int fq) const {
;     ...
;       for (int m = 0; m < 4; ++m) {
;         const float r = rs[m]; float v[8];
; #pragma unroll
;         for (int n = 0; n < 2; ++n)
; #pragma unroll
;           for (int c = 0; c < 4; ++c) { const float g = acc[ai][0][m][n][c] * r, uu = acc[ai][1][m][n][c] * r; v[4 * n + c] = g * sigm(g) * uu; }
;         u32x4 w; w.x = pk2(v[0], v[1]); w.y = pk2(v[2], v[3]); w.z = pk2(v[4], v[5]); w.w = pk2(v[6], v[7]);
;         *(u32x4*)(hbuf + (unsigned)(row0 + ai * 128 + m * 16) * DFF + col0) = w;
	v_exp_f32_e32 v207, v207
	v_pk_mul_f32 v[90:91], v[90:91], v[234:235]
	v_exp_f32_e32 v208, v208
	v_cvt_pk_bf16_f32 v236, v92, v93
	v_exp_f32_e32 v209, v209
	v_cvt_pk_bf16_f32 v237, v94, v95
	v_exp_f32_e32 v210, v210
	v_cvt_pk_bf16_f32 v238, v88, v89
	v_exp_f32_e32 v211, v211
	v_cvt_pk_bf16_f32 v239, v90, v91
	global_store_dwordx4 v[240:241], v[236:239], off
	v_lshl_add_u64 v[240:241], v[240:241], 0, s[100:101]
	v_pk_fma_f32 v[204:205], v[204:205], v[178:179], v[178:179] op_sel_hi:[1,0,0]
	v_pk_fma_f32 v[206:207], v[206:207], v[178:179], v[178:179] op_sel_hi:[1,0,0]
	v_pk_fma_f32 v[208:209], v[208:209], v[178:179], v[178:179] op_sel_hi:[1,0,0]
	v_pk_fma_f32 v[210:211], v[210:211], v[178:179], v[178:179] op_sel_hi:[1,0,0]
	v_rcp_f32_e32 v204, v204
	v_pk_mul_f32 v[228:229], v[60:61], v[196:197] op_sel_hi:[1,0]
	v_rcp_f32_e32 v205, v205
	v_pk_mul_f32 v[230:231], v[62:63], v[196:197] op_sel_hi:[1,0]
	v_rcp_f32_e32 v206, v206
	v_pk_mul_f32 v[232:233], v[56:57], v[196:197] op_sel_hi:[1,0]
	v_rcp_f32_e32 v207, v207
	v_pk_mul_f32 v[234:235], v[58:59], v[196:197] op_sel_hi:[1,0]
	v_rcp_f32_e32 v208, v208
	v_pk_mul_f32 v[60:61], v[60:61], v[52:53]
	v_rcp_f32_e32 v209, v209
	v_pk_mul_f32 v[62:63], v[62:63], v[54:55]
	v_rcp_f32_e32 v210, v210
	v_pk_mul_f32 v[56:57], v[56:57], v[48:49]
	v_rcp_f32_e32 v211, v211
	v_pk_mul_f32 v[58:59], v[58:59], v[50:51]
	v_exp_f32_e32 v228, v228
	v_pk_mul_f32 v[76:77], v[76:77], v[204:205]
	v_exp_f32_e32 v229, v229
	v_pk_mul_f32 v[78:79], v[78:79], v[206:207]
	v_exp_f32_e32 v230, v230
	v_pk_mul_f32 v[72:73], v[72:73], v[208:209]
	v_exp_f32_e32 v231, v231
	v_pk_mul_f32 v[74:75], v[74:75], v[210:211]
	v_exp_f32_e32 v232, v232
	v_cvt_pk_bf16_f32 v236, v76, v77
	v_exp_f32_e32 v233, v233
	v_cvt_pk_bf16_f32 v237, v78, v79
	v_exp_f32_e32 v234, v234
	v_cvt_pk_bf16_f32 v238, v72, v73
	v_exp_f32_e32 v235, v235
	v_cvt_pk_bf16_f32 v239, v74, v75
	global_store_dwordx4 v[240:241], v[236:239], off
	v_pk_fma_f32 v[228:229], v[228:229], v[180:181], v[180:181] op_sel_hi:[1,0,0]
	v_pk_fma_f32 v[230:231], v[230:231], v[180:181], v[180:181] op_sel_hi:[1,0,0]
	v_pk_fma_f32 v[232:233], v[232:233], v[180:181], v[180:181] op_sel_hi:[1,0,0]
	v_pk_fma_f32 v[234:235], v[234:235], v[180:181], v[180:181] op_sel_hi:[1,0,0]
	v_rcp_f32_e32 v228, v228
	v_pk_mul_f32 v[204:205], v[44:45], v[198:199] op_sel_hi:[1,0]
	v_rcp_f32_e32 v229, v229
	v_pk_mul_f32 v[206:207], v[46:47], v[198:199] op_sel_hi:[1,0]
	v_rcp_f32_e32 v230, v230
	v_pk_mul_f32 v[208:209], v[40:41], v[198:199] op_sel_hi:[1,0]
	v_rcp_f32_e32 v231, v231
	v_pk_mul_f32 v[210:211], v[42:43], v[198:199] op_sel_hi:[1,0]
	v_rcp_f32_e32 v232, v232
	v_pk_mul_f32 v[44:45], v[44:45], v[36:37]
	v_rcp_f32_e32 v233, v233
	v_pk_mul_f32 v[46:47], v[46:47], v[38:39]
	v_rcp_f32_e32 v234, v234
	v_pk_mul_f32 v[40:41], v[40:41], v[32:33]
	v_rcp_f32_e32 v235, v235
	v_pk_mul_f32 v[42:43], v[42:43], v[34:35]
	v_exp_f32_e32 v204, v204
	v_pk_mul_f32 v[60:61], v[60:61], v[228:229]
	v_exp_f32_e32 v205, v205
	v_pk_mul_f32 v[62:63], v[62:63], v[230:231]
	v_exp_f32_e32 v206, v206
	v_pk_mul_f32 v[56:57], v[56:57], v[232:233]
	v_exp_f32_e32 v207, v207
	v_pk_mul_f32 v[58:59], v[58:59], v[234:235]
	v_exp_f32_e32 v208, v208
	v_cvt_pk_bf16_f32 v236, v60, v61
	v_exp_f32_e32 v209, v209
	v_cvt_pk_bf16_f32 v237, v62, v63
	v_exp_f32_e32 v210, v210
	v_cvt_pk_bf16_f32 v238, v56, v57
	v_exp_f32_e32 v211, v211
	v_cvt_pk_bf16_f32 v239, v58, v59
	global_store_dwordx4 v[242:243], v[236:239], off
	v_lshl_add_u64 v[242:243], v[242:243], 0, s[100:101]
	v_pk_fma_f32 v[204:205], v[204:205], v[182:183], v[182:183] op_sel_hi:[1,0,0]
	v_pk_fma_f32 v[206:207], v[206:207], v[182:183], v[182:183] op_sel_hi:[1,0,0]
	v_pk_fma_f32 v[208:209], v[208:209], v[182:183], v[182:183] op_sel_hi:[1,0,0]
	v_pk_fma_f32 v[210:211], v[210:211], v[182:183], v[182:183] op_sel_hi:[1,0,0]
	v_rcp_f32_e32 v204, v204
; __device__ __forceinline__ unsigned pk2(float lo, float hi) { f32x2_t v = {lo, hi}; bf16x2_t b = __builtin_convertvector(v, bf16x2_t); return __builtin_bit_cast(unsigned, b); }
; __device__ __forceinline__ float sigm(float x) { return frcp(1.f + fexp2(-LOG2E * x)); }
; #define PG8_BAR __builtin_amdgcn_s_barrier()
; template <class Epi, class Sched, bool ALIGN_EPI = false, bool SP2 = false, bool F16 = false, bool TOKPERM = false>
; __device__ __forceinline__ void gemm_phase(PG8_LAS unsigned char* lds, const Gemm g, const Sched& S, const Epi& E, int wv) {
;     ...
;         if constexpr (ALIGN_EPI) { if (wr == 0) PG8_BAR; }
;         if constexpr (!Epi::AFTER_DRAIN) { E(acc, cur, wr, wc, fr, fq); S.done(cur); }
;         if (!has_next) break;
; #pragma unroll
;         for (int a = 0; a < 2; ++a)
; #pragma unroll
;             for (int b = 0; b < 2; ++b)
; #pragma unroll
;                 for (int m = 0; m < 4; ++m)
; #pragma unroll
;                     for (int n = 0; n < 2; ++n) acc[a][b][m][n] = (f32x4){0.f, 0.f, 0.f, 0.f};
;         cur = nxt; cA = nA; cB = nB; ++ui;
;         if constexpr (ALIGN_EPI) { if (wr == 1) PG8_BAR; }
;   __device__ __forceinline__ void operator()(const pg8::f32x4 (&acc)[2][2][4][2], const pg8::Unit& u, int wr, int wc, int fr, int fq) const {
;     ...
;       for (int m = 0; m < 4; ++m) {
;         const float r = rs[m]; float v[8];
; #pragma unroll
;         for (int n = 0; n < 2; ++n)
; #pragma unroll
;           for (int c = 0; c < 4; ++c) { const float g = acc[ai][0][m][n][c] * r, uu = acc[ai][1][m][n][c] * r; v[4 * n + c] = g * sigm(g) * uu; }
;         u32x4 w; w.x = pk2(v[0], v[1]); w.y = pk2(v[2], v[3]); w.z = pk2(v[4], v[5]); w.w = pk2(v[6], v[7]);
;         *(u32x4*)(hbuf + (unsigned)(row0 + ai * 128 + m * 16) * DFF + col0) = w;
	v_pk_mul_f32 v[228:229], v[28:29], v[200:201] op_sel_hi:[1,0]
	v_rcp_f32_e32 v205, v205
	v_pk_mul_f32 v[230:231], v[30:31], v[200:201] op_sel_hi:[1,0]
	v_rcp_f32_e32 v206, v206
	v_pk_mul_f32 v[232:233], v[24:25], v[200:201] op_sel_hi:[1,0]
	v_rcp_f32_e32 v207, v207
	v_pk_mul_f32 v[234:235], v[26:27], v[200:201] op_sel_hi:[1,0]
	v_rcp_f32_e32 v208, v208
	v_pk_mul_f32 v[28:29], v[28:29], v[20:21]
	v_rcp_f32_e32 v209, v209
	v_pk_mul_f32 v[30:31], v[30:31], v[22:23]
	v_rcp_f32_e32 v210, v210
	v_pk_mul_f32 v[24:25], v[24:25], v[16:17]
	v_rcp_f32_e32 v211, v211
	v_pk_mul_f32 v[26:27], v[26:27], v[18:19]
	v_exp_f32_e32 v228, v228
	v_pk_mul_f32 v[44:45], v[44:45], v[204:205]
	v_exp_f32_e32 v229, v229
	v_pk_mul_f32 v[46:47], v[46:47], v[206:207]
	v_exp_f32_e32 v230, v230
	v_pk_mul_f32 v[40:41], v[40:41], v[208:209]
	v_exp_f32_e32 v231, v231
	v_pk_mul_f32 v[42:43], v[42:43], v[210:211]
	v_exp_f32_e32 v232, v232
	v_cvt_pk_bf16_f32 v236, v44, v45
	v_exp_f32_e32 v233, v233
	v_cvt_pk_bf16_f32 v237, v46, v47
	v_exp_f32_e32 v234, v234
	v_cvt_pk_bf16_f32 v238, v40, v41
	v_exp_f32_e32 v235, v235
	v_cvt_pk_bf16_f32 v239, v42, v43
	global_store_dwordx4 v[242:243], v[236:239], off
	v_lshl_add_u64 v[242:243], v[242:243], 0, s[100:101]
	v_pk_fma_f32 v[228:229], v[228:229], v[184:185], v[184:185] op_sel_hi:[1,0,0]
	v_pk_fma_f32 v[230:231], v[230:231], v[184:185], v[184:185] op_sel_hi:[1,0,0]
	v_pk_fma_f32 v[232:233], v[232:233], v[184:185], v[184:185] op_sel_hi:[1,0,0]
	v_pk_fma_f32 v[234:235], v[234:235], v[184:185], v[184:185] op_sel_hi:[1,0,0]
	v_rcp_f32_e32 v228, v228
	v_pk_mul_f32 v[204:205], v[12:13], v[202:203] op_sel_hi:[1,0]
	v_rcp_f32_e32 v229, v229
	v_pk_mul_f32 v[206:207], v[14:15], v[202:203] op_sel_hi:[1,0]
	v_rcp_f32_e32 v230, v230
	v_pk_mul_f32 v[208:209], v[8:9], v[202:203] op_sel_hi:[1,0]
	v_rcp_f32_e32 v231, v231
	v_pk_mul_f32 v[210:211], v[10:11], v[202:203] op_sel_hi:[1,0]
	v_rcp_f32_e32 v232, v232
	v_pk_mul_f32 v[12:13], v[12:13], v[4:5]
	v_rcp_f32_e32 v233, v233
	v_pk_mul_f32 v[14:15], v[14:15], v[6:7]
	v_rcp_f32_e32 v234, v234
	v_pk_mul_f32 v[8:9], v[8:9], v[0:1]
	v_rcp_f32_e32 v235, v235
	v_pk_mul_f32 v[10:11], v[10:11], v[2:3]
	v_exp_f32_e32 v204, v204
	v_pk_mul_f32 v[28:29], v[28:29], v[228:229]
	v_exp_f32_e32 v205, v205
	v_pk_mul_f32 v[30:31], v[30:31], v[230:231]
	v_exp_f32_e32 v206, v206
	v_pk_mul_f32 v[24:25], v[24:25], v[232:233]
	v_exp_f32_e32 v207, v207
	v_pk_mul_f32 v[26:27], v[26:27], v[234:235]
	v_exp_f32_e32 v208, v208
	v_cvt_pk_bf16_f32 v236, v28, v29
	v_exp_f32_e32 v209, v209
	v_cvt_pk_bf16_f32 v237, v30, v31
	v_exp_f32_e32 v210, v210
	v_cvt_pk_bf16_f32 v238, v24, v25
	v_exp_f32_e32 v211, v211
	v_cvt_pk_bf16_f32 v239, v26, v27
	global_store_dwordx4 v[242:243], v[236:239], off
	v_lshl_add_u64 v[242:243], v[242:243], 0, s[100:101]
	v_pk_fma_f32 v[204:205], v[204:205], v[186:187], v[186:187] op_sel_hi:[1,0,0]
	v_pk_fma_f32 v[206:207], v[206:207], v[186:187], v[186:187] op_sel_hi:[1,0,0]
	v_pk_fma_f32 v[208:209], v[208:209], v[186:187], v[186:187] op_sel_hi:[1,0,0]
	v_pk_fma_f32 v[210:211], v[210:211], v[186:187], v[186:187] op_sel_hi:[1,0,0]
	v_rcp_f32_e32 v204, v204
	v_rcp_f32_e32 v205, v205
	v_rcp_f32_e32 v206, v206
	v_rcp_f32_e32 v207, v207
	v_rcp_f32_e32 v208, v208
	v_rcp_f32_e32 v209, v209
	v_rcp_f32_e32 v210, v210
	v_rcp_f32_e32 v211, v211
	v_pk_mul_f32 v[12:13], v[12:13], v[204:205]
	v_pk_mul_f32 v[14:15], v[14:15], v[206:207]
	v_pk_mul_f32 v[8:9], v[8:9], v[208:209]
	v_pk_mul_f32 v[10:11], v[10:11], v[210:211]
	v_cvt_pk_bf16_f32 v236, v12, v13
	v_cvt_pk_bf16_f32 v237, v14, v15
	v_cvt_pk_bf16_f32 v238, v8, v9
	v_cvt_pk_bf16_f32 v239, v10, v11
	global_store_dwordx4 v[242:243], v[236:239], off
	s_andn2_b64 vcc, exec, s[4:5]
	s_mov_b64 s[4:5], -1
	s_cbranch_vccnz .LBB0_1603
	s_andn2_b64 vcc, exec, s[12:13]
	s_cbranch_vccnz .LBB0_1602
	s_barrier
	s_branch .LBB0_1602
